# hand-written radix-16 forward LQ=10 FFT pass only
# speedup vs baseline: 1.0120x; 1.0048x over previous
; template <bool INV> __device__ __forceinline__ void dft4(cf& a0, cf& a1, cf& a2, cf& a3) {
;     const cf t0 = cadd(a0, a2), t1 = csub(a0, a2), t2 = cadd(a1, a3), t3 = csub(a1, a3);
;     a0 = cadd(t0, t2); a2 = csub(t0, t2);
;     if (!INV) { a1 = {t1.x + t3.y, t1.y - t3.x}; a3 = {t1.x - t3.y, t1.y + t3.x}; }
;     else      { a1 = {t1.x - t3.y, t1.y + t3.x}; a3 = {t1.x + t3.y, t1.y - t3.x}; }
; }
; template <bool INV> __device__ __forceinline__ void dft16(cf (&a)[16]) {
; #pragma unroll
;     for (int n2 = 0; n2 < 4; ++n2) dft4<INV>(a[n2], a[4 + n2], a[8 + n2], a[12 + n2]);
; #pragma unroll
;     for (int k1 = 1; k1 < 4; ++k1)
; #pragma unroll
;         for (int n2 = 1; n2 < 4; ++n2) { const cf w = {W16C(n2 * k1), W16S(n2 * k1)};
;             a[4 * k1 + n2] = INV ? cmul(a[4 * k1 + n2], w) : cmulc(a[4 * k1 + n2], w); }
; #pragma unroll
;     for (int k1 = 0; k1 < 4; ++k1) dft4<INV>(a[4 * k1 + 0], a[4 * k1 + 1], a[4 * k1 + 2], a[4 * k1 + 3]);
; }
; template <bool INV, int LQ> __device__ __forceinline__ void fft_pass16(f32x2* X, int tid) {
;     constexpr int q = 1 << LQ, STR = q + 4 * (q >> 6);
; #pragma unroll 1
;     for (int gg = 0; gg < 2; ++gg) {
;         const int g = tid + 512 * gg, blk = g >> LQ, i = g & (q - 1), base = (blk << (LQ + 4)) + i;
;         f32x2* xb = X + fidx(base);
;         cf a[16];
; #pragma unroll
;         for (int j = 0; j < 16; ++j) { const f32x2 v = xb[j * STR]; a[j] = {v.x, v.y}; }
;         const float rev = (float)i * (1.f / (float)(16 << LQ));
;         const cf w1 = {__builtin_amdgcn_cosf(rev), __builtin_amdgcn_sinf(rev)};
;         if (!INV) {
;             dft16<false>(a);
;             cf w = w1;
; #pragma unroll
;             for (int k = 1; k < 16; ++k) { const int src = 4 * (k & 3) + (k >> 2);
;                 const cf y = cmulc(a[src], w); xb[k * STR] = (f32x2){y.x, y.y}; w = cmul(w, w1); }
.LBB0_279:
	v_add_u32_e32 v0, s24, v240
	v_and_b32_e32 v0, 0x3ff, v0
	v_lshrrev_b32_e32 v1, 6, v0
	v_lshl_add_u32 v1, v1, 2, v0
	v_lshlrev_b32_e32 v1, 3, v1
	v_add_u32_e32 v2, 0x11000, v1
	ds_read_b64 v[170:171], v1
	ds_read_b64 v[172:173], v1 offset:8704
	ds_read_b64 v[174:175], v1 offset:17408
	ds_read_b64 v[176:177], v1 offset:26112
	ds_read_b64 v[178:179], v1 offset:34816
	ds_read_b64 v[180:181], v1 offset:43520
	ds_read_b64 v[182:183], v1 offset:52224
	ds_read_b64 v[184:185], v1 offset:60928
	ds_read_b64 v[186:187], v2
	ds_read_b64 v[188:189], v2 offset:8704
	ds_read_b64 v[190:191], v2 offset:17408
	ds_read_b64 v[192:193], v2 offset:26112
	ds_read_b64 v[194:195], v2 offset:34816
	ds_read_b64 v[196:197], v2 offset:43520
	ds_read_b64 v[198:199], v2 offset:52224
	ds_read_b64 v[200:201], v2 offset:60928
	v_cvt_f32_u32_e32 v3, v0
	v_mul_f32_e32 v3, 0x38800000, v3
	v_sin_f32_e32 v4, v3
	v_cos_f32_e32 v3, v3
	s_waitcnt lgkmcnt(0)
	v_add_f32_e32 v202, v170, v186
	v_add_f32_e32 v203, v171, v187
	v_sub_f32_e32 v204, v170, v186
	v_sub_f32_e32 v205, v171, v187
	v_add_f32_e32 v18, v178, v194
	v_add_f32_e32 v19, v179, v195
	v_sub_f32_e32 v20, v178, v194
	v_sub_f32_e32 v21, v179, v195
	v_add_f32_e32 v170, v202, v18
	v_add_f32_e32 v171, v203, v19
	v_sub_f32_e32 v186, v202, v18
	v_sub_f32_e32 v187, v203, v19
	v_add_f32_e32 v178, v204, v21
	v_sub_f32_e32 v179, v205, v20
	v_sub_f32_e32 v194, v204, v21
	v_add_f32_e32 v195, v205, v20
	v_add_f32_e32 v22, v172, v188
	v_add_f32_e32 v23, v173, v189
	v_sub_f32_e32 v24, v172, v188
	v_sub_f32_e32 v25, v173, v189
	v_add_f32_e32 v26, v180, v196
	v_add_f32_e32 v27, v181, v197
	v_sub_f32_e32 v28, v180, v196
	v_sub_f32_e32 v29, v181, v197
	v_add_f32_e32 v172, v22, v26
	v_add_f32_e32 v173, v23, v27
	v_sub_f32_e32 v188, v22, v26
	v_sub_f32_e32 v189, v23, v27
	v_add_f32_e32 v180, v24, v29
	v_sub_f32_e32 v181, v25, v28
	v_sub_f32_e32 v196, v24, v29
	v_add_f32_e32 v197, v25, v28
	v_add_f32_e32 v30, v174, v190
	v_add_f32_e32 v31, v175, v191
	v_sub_f32_e32 v32, v174, v190
	v_sub_f32_e32 v33, v175, v191
	v_add_f32_e32 v138, v182, v198
	v_add_f32_e32 v139, v183, v199
	v_sub_f32_e32 v140, v182, v198
	v_sub_f32_e32 v141, v183, v199
	v_add_f32_e32 v174, v30, v138
	v_add_f32_e32 v175, v31, v139
	v_sub_f32_e32 v190, v30, v138
	v_sub_f32_e32 v191, v31, v139
	v_add_f32_e32 v182, v32, v141
	v_sub_f32_e32 v183, v33, v140
	v_sub_f32_e32 v198, v32, v141
	v_add_f32_e32 v199, v33, v140
	v_add_f32_e32 v202, v176, v192
	v_add_f32_e32 v203, v177, v193
	v_sub_f32_e32 v204, v176, v192
	v_sub_f32_e32 v205, v177, v193
	v_add_f32_e32 v18, v184, v200
	v_add_f32_e32 v19, v185, v201
	v_sub_f32_e32 v20, v184, v200
	v_sub_f32_e32 v21, v185, v201
	v_add_f32_e32 v176, v202, v18
	v_add_f32_e32 v177, v203, v19
	v_sub_f32_e32 v192, v202, v18
	v_sub_f32_e32 v193, v203, v19
	v_add_f32_e32 v184, v204, v21
	v_sub_f32_e32 v185, v205, v20
	v_sub_f32_e32 v200, v204, v21
	v_add_f32_e32 v201, v205, v20
	v_mul_f32_e32 v22, s67, v180
	v_mul_f32_e32 v23, s67, v181
	v_fmac_f32_e32 v22, s66, v181
	v_fma_f32 v23, -v180, s66, v23
	v_add_f32_e32 v24, v182, v183
	v_sub_f32_e32 v25, v183, v182
	v_mul_f32_e32 v24, s70, v24
	v_mul_f32_e32 v25, s70, v25
	v_mul_f32_e32 v26, s66, v184
	v_mul_f32_e32 v27, s66, v185
	v_fmac_f32_e32 v26, s67, v185
	v_fma_f32 v27, -v184, s67, v27
	v_add_f32_e32 v28, v188, v189
	v_sub_f32_e32 v29, v189, v188
	v_mul_f32_e32 v28, s70, v28
	v_mul_f32_e32 v29, s70, v29
	v_mov_b32_e32 v30, v191
	v_xor_b32_e32 v31, 0x80000000, v190
	v_sub_f32_e32 v32, v193, v192
	v_add_f32_e32 v33, v192, v193
	v_mul_f32_e32 v32, s70, v32
	v_mul_f32_e32 v33, s71, v33
	v_mul_f32_e32 v138, s66, v196
	v_mul_f32_e32 v139, s66, v197
	v_fmac_f32_e32 v138, s67, v197
	v_fma_f32 v139, -v196, s67, v139
	v_sub_f32_e32 v140, v199, v198
	v_add_f32_e32 v141, v198, v199
	v_mul_f32_e32 v140, s70, v140
	v_mul_f32_e32 v141, s71, v141
	v_mul_f32_e32 v202, s67, v200
	v_mul_f32_e32 v203, s67, v201
	v_fmac_f32_e32 v202, s66, v201
	v_fma_f32 v203, -v200, s66, v203
	v_xor_b32_e32 v202, 0x80000000, v202
	v_xor_b32_e32 v203, 0x80000000, v203
	v_add_f32_e32 v204, v170, v174
	v_add_f32_e32 v205, v171, v175
	v_sub_f32_e32 v18, v170, v174
	v_sub_f32_e32 v19, v171, v175
	v_add_f32_e32 v20, v172, v176
	v_add_f32_e32 v21, v173, v177
	v_sub_f32_e32 v180, v172, v176
	v_sub_f32_e32 v181, v173, v177
	v_add_f32_e32 v170, v204, v20
	v_add_f32_e32 v171, v205, v21
	v_sub_f32_e32 v174, v204, v20
	v_sub_f32_e32 v175, v205, v21
	v_add_f32_e32 v172, v18, v181
	v_sub_f32_e32 v173, v19, v180
	v_sub_f32_e32 v176, v18, v181
	v_add_f32_e32 v177, v19, v180
	v_add_f32_e32 v182, v178, v24
	v_add_f32_e32 v183, v179, v25
	v_sub_f32_e32 v184, v178, v24
	v_sub_f32_e32 v185, v179, v25
	v_add_f32_e32 v188, v22, v26
	v_add_f32_e32 v189, v23, v27
	v_sub_f32_e32 v190, v22, v26
	v_sub_f32_e32 v191, v23, v27
	v_add_f32_e32 v178, v182, v188
	v_add_f32_e32 v179, v183, v189
	v_sub_f32_e32 v24, v182, v188
	v_sub_f32_e32 v25, v183, v189
	v_add_f32_e32 v22, v184, v191
	v_sub_f32_e32 v23, v185, v190
	v_sub_f32_e32 v26, v184, v191
	v_add_f32_e32 v27, v185, v190
	v_add_f32_e32 v192, v186, v30
	v_add_f32_e32 v193, v187, v31
	v_sub_f32_e32 v196, v186, v30
; template <bool INV> __device__ __forceinline__ void dft16(cf (&a)[16]) {
; #pragma unroll
;     for (int n2 = 0; n2 < 4; ++n2) dft4<INV>(a[n2], a[4 + n2], a[8 + n2], a[12 + n2]);
; #pragma unroll
;     for (int k1 = 1; k1 < 4; ++k1)
; #pragma unroll
;         for (int n2 = 1; n2 < 4; ++n2) { const cf w = {W16C(n2 * k1), W16S(n2 * k1)};
;             a[4 * k1 + n2] = INV ? cmul(a[4 * k1 + n2], w) : cmulc(a[4 * k1 + n2], w); }
; #pragma unroll
;     for (int k1 = 0; k1 < 4; ++k1) dft4<INV>(a[4 * k1 + 0], a[4 * k1 + 1], a[4 * k1 + 2], a[4 * k1 + 3]);
; }
; template <bool INV, int LQ> __device__ __forceinline__ void fft_pass16(f32x2* X, int tid) {
;     ...
;         if (!INV) {
;             dft16<false>(a);
;             cf w = w1;
; #pragma unroll
;             for (int k = 1; k < 16; ++k) { const int src = 4 * (k & 3) + (k >> 2);
;                 const cf y = cmulc(a[src], w); xb[k * STR] = (f32x2){y.x, y.y}; w = cmul(w, w1); }
;             xb[0] = (f32x2){a[0].x, a[0].y};
	v_sub_f32_e32 v197, v187, v31
	v_add_f32_e32 v198, v28, v32
	v_add_f32_e32 v199, v29, v33
	v_sub_f32_e32 v200, v28, v32
	v_sub_f32_e32 v201, v29, v33
	v_add_f32_e32 v186, v192, v198
	v_add_f32_e32 v187, v193, v199
	v_sub_f32_e32 v30, v192, v198
	v_sub_f32_e32 v31, v193, v199
	v_add_f32_e32 v28, v196, v201
	v_sub_f32_e32 v29, v197, v200
	v_sub_f32_e32 v32, v196, v201
	v_add_f32_e32 v33, v197, v200
	v_add_f32_e32 v204, v194, v140
	v_add_f32_e32 v205, v195, v141
	v_sub_f32_e32 v18, v194, v140
	v_sub_f32_e32 v19, v195, v141
	v_add_f32_e32 v20, v138, v202
	v_add_f32_e32 v21, v139, v203
	v_sub_f32_e32 v180, v138, v202
	v_sub_f32_e32 v181, v139, v203
	v_add_f32_e32 v194, v204, v20
	v_add_f32_e32 v195, v205, v21
	v_sub_f32_e32 v140, v204, v20
	v_sub_f32_e32 v141, v205, v21
	v_add_f32_e32 v138, v18, v181
	v_sub_f32_e32 v139, v19, v180
	v_sub_f32_e32 v202, v18, v181
	v_add_f32_e32 v203, v19, v180
	ds_write_b64 v1, v[170:171]
	v_mul_f32_e32 v182, v178, v3
	v_mul_f32_e32 v183, v179, v3
	v_fmac_f32_e32 v182, v179, v4
	v_fma_f32 v183, -v178, v4, v183
	ds_write_b64 v1, v[182:183] offset:8704
	v_mul_f32_e32 v5, v3, v3
	v_mul_f32_e32 v6, v3, v4
	v_fma_f32 v5, -v4, v4, v5
	v_fmac_f32_e32 v6, v4, v3
	v_mul_f32_e32 v184, v186, v5
	v_mul_f32_e32 v185, v187, v5
	v_fmac_f32_e32 v184, v187, v6
	v_fma_f32 v185, -v186, v6, v185
	ds_write_b64 v1, v[184:185] offset:17408
	v_mul_f32_e32 v7, v5, v3
	v_mul_f32_e32 v8, v5, v4
	v_fma_f32 v7, -v6, v4, v7
	v_fmac_f32_e32 v8, v6, v3
	v_mul_f32_e32 v188, v194, v7
	v_mul_f32_e32 v189, v195, v7
	v_fmac_f32_e32 v188, v195, v8
	v_fma_f32 v189, -v194, v8, v189
	ds_write_b64 v1, v[188:189] offset:26112
	v_mul_f32_e32 v5, v7, v3
	v_mul_f32_e32 v6, v7, v4
	v_fma_f32 v5, -v8, v4, v5
	v_fmac_f32_e32 v6, v8, v3
	v_mul_f32_e32 v190, v172, v5
	v_mul_f32_e32 v191, v173, v5
	v_fmac_f32_e32 v190, v173, v6
	v_fma_f32 v191, -v172, v6, v191
	ds_write_b64 v1, v[190:191] offset:34816
	v_mul_f32_e32 v7, v5, v3
	v_mul_f32_e32 v8, v5, v4
	v_fma_f32 v7, -v6, v4, v7
	v_fmac_f32_e32 v8, v6, v3
	v_mul_f32_e32 v192, v22, v7
	v_mul_f32_e32 v193, v23, v7
	v_fmac_f32_e32 v192, v23, v8
	v_fma_f32 v193, -v22, v8, v193
	ds_write_b64 v1, v[192:193] offset:43520
	v_mul_f32_e32 v5, v7, v3
	v_mul_f32_e32 v6, v7, v4
	v_fma_f32 v5, -v8, v4, v5
	v_fmac_f32_e32 v6, v8, v3
	v_mul_f32_e32 v196, v28, v5
	v_mul_f32_e32 v197, v29, v5
	v_fmac_f32_e32 v196, v29, v6
	v_fma_f32 v197, -v28, v6, v197
	ds_write_b64 v1, v[196:197] offset:52224
	v_mul_f32_e32 v7, v5, v3
	v_mul_f32_e32 v8, v5, v4
	v_fma_f32 v7, -v6, v4, v7
	v_fmac_f32_e32 v8, v6, v3
	v_mul_f32_e32 v198, v138, v7
	v_mul_f32_e32 v199, v139, v7
	v_fmac_f32_e32 v198, v139, v8
	v_fma_f32 v199, -v138, v8, v199
	ds_write_b64 v1, v[198:199] offset:60928
	v_mul_f32_e32 v5, v7, v3
	v_mul_f32_e32 v6, v7, v4
	v_fma_f32 v5, -v8, v4, v5
	v_fmac_f32_e32 v6, v8, v3
	v_mul_f32_e32 v200, v174, v5
	v_mul_f32_e32 v201, v175, v5
	v_fmac_f32_e32 v200, v175, v6
	v_fma_f32 v201, -v174, v6, v201
	ds_write_b64 v2, v[200:201]
	v_mul_f32_e32 v7, v5, v3
	v_mul_f32_e32 v8, v5, v4
	v_fma_f32 v7, -v6, v4, v7
	v_fmac_f32_e32 v8, v6, v3
	v_mul_f32_e32 v204, v24, v7
	v_mul_f32_e32 v205, v25, v7
	v_fmac_f32_e32 v204, v25, v8
	v_fma_f32 v205, -v24, v8, v205
	ds_write_b64 v2, v[204:205] offset:8704
	v_mul_f32_e32 v5, v7, v3
	v_mul_f32_e32 v6, v7, v4
	v_fma_f32 v5, -v8, v4, v5
	v_fmac_f32_e32 v6, v8, v3
	v_mul_f32_e32 v18, v30, v5
	v_mul_f32_e32 v19, v31, v5
	v_fmac_f32_e32 v18, v31, v6
	v_fma_f32 v19, -v30, v6, v19
	ds_write_b64 v2, v[18:19] offset:17408
	v_mul_f32_e32 v7, v5, v3
	v_mul_f32_e32 v8, v5, v4
	v_fma_f32 v7, -v6, v4, v7
	v_fmac_f32_e32 v8, v6, v3
	v_mul_f32_e32 v20, v140, v7
	v_mul_f32_e32 v21, v141, v7
	v_fmac_f32_e32 v20, v141, v8
	v_fma_f32 v21, -v140, v8, v21
	ds_write_b64 v2, v[20:21] offset:26112
	v_mul_f32_e32 v5, v7, v3
	v_mul_f32_e32 v6, v7, v4
	v_fma_f32 v5, -v8, v4, v5
	v_fmac_f32_e32 v6, v8, v3
	v_mul_f32_e32 v180, v176, v5
	v_mul_f32_e32 v181, v177, v5
	v_fmac_f32_e32 v180, v177, v6
	v_fma_f32 v181, -v176, v6, v181
	ds_write_b64 v2, v[180:181] offset:34816
	v_mul_f32_e32 v7, v5, v3
	v_mul_f32_e32 v8, v5, v4
	v_fma_f32 v7, -v6, v4, v7
	v_fmac_f32_e32 v8, v6, v3
	v_mul_f32_e32 v178, v26, v7
	v_mul_f32_e32 v179, v27, v7
	v_fmac_f32_e32 v178, v27, v8
	v_fma_f32 v179, -v26, v8, v179
	ds_write_b64 v2, v[178:179] offset:43520
	v_mul_f32_e32 v5, v7, v3
	v_mul_f32_e32 v6, v7, v4
	v_fma_f32 v5, -v8, v4, v5
	v_fmac_f32_e32 v6, v8, v3
	v_mul_f32_e32 v182, v32, v5
	v_mul_f32_e32 v183, v33, v5
	v_fmac_f32_e32 v182, v33, v6
	v_fma_f32 v183, -v32, v6, v183
	ds_write_b64 v2, v[182:183] offset:52224
	v_mul_f32_e32 v7, v5, v3
	v_mul_f32_e32 v8, v5, v4
	v_fma_f32 v7, -v6, v4, v7
	v_fmac_f32_e32 v8, v6, v3
	v_mul_f32_e32 v186, v202, v7
	v_mul_f32_e32 v187, v203, v7
	v_fmac_f32_e32 v186, v203, v8
	v_fma_f32 v187, -v202, v8, v187
	ds_write_b64 v2, v[186:187] offset:60928
	s_mov_b32 s48, s67
	s_mov_b32 s49, s66
	s_mov_b32 s64, s25
	s_mov_b32 s65, s71
	s_mov_b32 s24, s71
	s_mov_b32 s48, s70
	s_mov_b32 s61, s71
	s_movk_i32 s24, 0x200
	s_and_b64 vcc, exec, s[38:39]
	s_mov_b64 s[38:39], 0
	s_cbranch_vccnz .LBB0_279
	s_mov_b32 s93, 0
	s_mov_b64 s[38:39], -1
	s_waitcnt lgkmcnt(0)
	s_barrier
